# FFN K-loops: m0-write -> LDS-DMA wait state filled with a ds_read_b128 of the same segment instead of s_nop 0, the two segment waits merged into one s_waitcnt (16 fewer s_nop and 4 fewer waits per ite
# speedup vs baseline: 1.0068x; 1.0068x over previous
.LBB0_182:
	ds_read_b128 v[144:147], v153 offset:0
	ds_read_b128 v[156:159], v153 offset:1024
	ds_read_b128 v[160:163], v153 offset:2048
	ds_read_b128 v[164:167], v153 offset:3072
	ds_read_b128 v[168:171], v154 offset:0
	ds_read_b128 v[172:175], v154 offset:1024
	ds_read_b128 v[176:179], v154 offset:2048
	ds_read_b128 v[180:183], v154 offset:3072
	s_add_u32 s30, s72, 0xfff00080
	s_addc_u32 s31, s73, -1
	s_cmp_eq_u32 s41, 60
	s_cselect_b32 s31, s13, s31
	s_cselect_b32 s30, s37, s30
	s_cselect_b32 s75, s11, s40
	s_cselect_b32 s74, s38, s39
	ds_read_b128 v[184:187], v155 offset:0
	ds_read_b128 v[188:191], v155 offset:1024
	ds_read_b128 v[192:195], v155 offset:2048
	ds_read_b128 v[196:199], v155 offset:3072
	ds_read_b128 v[200:203], v155 offset:4096
	ds_read_b128 v[204:207], v155 offset:5120
	s_add_i32 m0, s29, 0xc000
	ds_read_b128 v[208:211], v155 offset:6144
	global_load_lds_dwordx4 v136, s[72:73]
	s_add_i32 m0, s29, 0xe000
	ds_read_b128 v[212:215], v155 offset:7168
	global_load_lds_dwordx4 v138, s[72:73]
	s_waitcnt vmcnt(8) lgkmcnt(0)
	s_barrier
	v_mfma_f32_16x16x32_bf16 v[124:127], v[144:147], v[184:187], v[124:127]
	v_mfma_f32_16x16x32_bf16 v[120:123], v[160:163], v[184:187], v[120:123]
	v_mfma_f32_16x16x32_bf16 v[108:111], v[144:147], v[192:195], v[108:111]
	v_mfma_f32_16x16x32_bf16 v[104:107], v[160:163], v[192:195], v[104:107]
	v_mfma_f32_16x16x32_bf16 v[92:95], v[144:147], v[200:203], v[92:95]
	v_mfma_f32_16x16x32_bf16 v[88:91], v[160:163], v[200:203], v[88:91]
	v_mfma_f32_16x16x32_bf16 v[76:79], v[144:147], v[208:211], v[76:79]
	v_mfma_f32_16x16x32_bf16 v[72:75], v[160:163], v[208:211], v[72:75]
	v_mfma_f32_16x16x32_bf16 v[124:127], v[156:159], v[188:191], v[124:127]
	v_mfma_f32_16x16x32_bf16 v[120:123], v[164:167], v[188:191], v[120:123]
	v_mfma_f32_16x16x32_bf16 v[108:111], v[156:159], v[196:199], v[108:111]
	v_mfma_f32_16x16x32_bf16 v[104:107], v[164:167], v[196:199], v[104:107]
	v_mfma_f32_16x16x32_bf16 v[92:95], v[156:159], v[204:207], v[92:95]
	v_mfma_f32_16x16x32_bf16 v[88:91], v[164:167], v[204:207], v[88:91]
	v_mfma_f32_16x16x32_bf16 v[76:79], v[156:159], v[212:215], v[76:79]
	v_mfma_f32_16x16x32_bf16 v[72:75], v[164:167], v[212:215], v[72:75]
	v_mfma_f32_16x16x32_bf16 v[116:119], v[168:171], v[184:187], v[116:119]
	v_mfma_f32_16x16x32_bf16 v[112:115], v[176:179], v[184:187], v[112:115]
	v_mfma_f32_16x16x32_bf16 v[100:103], v[168:171], v[192:195], v[100:103]
	v_mfma_f32_16x16x32_bf16 v[96:99], v[176:179], v[192:195], v[96:99]
	v_mfma_f32_16x16x32_bf16 v[84:87], v[168:171], v[200:203], v[84:87]
	v_mfma_f32_16x16x32_bf16 v[80:83], v[176:179], v[200:203], v[80:83]
	v_mfma_f32_16x16x32_bf16 v[68:71], v[168:171], v[208:211], v[68:71]
	v_mfma_f32_16x16x32_bf16 v[64:67], v[176:179], v[208:211], v[64:67]
	v_mfma_f32_16x16x32_bf16 v[116:119], v[172:175], v[188:191], v[116:119]
	v_mfma_f32_16x16x32_bf16 v[112:115], v[180:183], v[188:191], v[112:115]
	v_mfma_f32_16x16x32_bf16 v[100:103], v[172:175], v[196:199], v[100:103]
	v_mfma_f32_16x16x32_bf16 v[96:99], v[180:183], v[196:199], v[96:99]
	v_mfma_f32_16x16x32_bf16 v[84:87], v[172:175], v[204:207], v[84:87]
	v_mfma_f32_16x16x32_bf16 v[80:83], v[180:183], v[204:207], v[80:83]
	v_mfma_f32_16x16x32_bf16 v[68:71], v[172:175], v[212:215], v[68:71]
	v_mfma_f32_16x16x32_bf16 v[64:67], v[180:183], v[212:215], v[64:67]
	s_barrier
	s_add_u32 s42, s74, 0x100000
	s_addc_u32 s43, s75, 0
	ds_read_b128 v[184:187], v155 offset:16384
	ds_read_b128 v[188:191], v155 offset:17408
	s_add_i32 m0, s29, 0x10000
	ds_read_b128 v[192:195], v155 offset:18432
	global_load_lds_dwordx4 v130, s[74:75]
	s_add_i32 m0, s29, 0x12000
	ds_read_b128 v[196:199], v155 offset:19456
	global_load_lds_dwordx4 v134, s[74:75]
	s_add_i32 m0, s29, 0x14000
	ds_read_b128 v[200:203], v155 offset:20480
	global_load_lds_dwordx4 v130, s[42:43]
	s_add_i32 m0, s29, 0x16000
	ds_read_b128 v[204:207], v155 offset:21504
	global_load_lds_dwordx4 v134, s[42:43]
	s_add_i32 m0, s29, 0x0
	ds_read_b128 v[208:211], v155 offset:22528
	global_load_lds_dwordx4 v128, s[30:31]
	s_add_i32 m0, s29, 0x2000
	ds_read_b128 v[212:215], v155 offset:23552
	global_load_lds_dwordx4 v132, s[30:31]
	s_waitcnt vmcnt(8) lgkmcnt(0)
	s_barrier
	v_mfma_f32_16x16x32_bf16 v[60:63], v[144:147], v[184:187], v[60:63]
	v_mfma_f32_16x16x32_bf16 v[56:59], v[160:163], v[184:187], v[56:59]
	v_mfma_f32_16x16x32_bf16 v[44:47], v[144:147], v[192:195], v[44:47]
	v_mfma_f32_16x16x32_bf16 v[40:43], v[160:163], v[192:195], v[40:43]
	v_mfma_f32_16x16x32_bf16 v[28:31], v[144:147], v[200:203], v[28:31]
	v_mfma_f32_16x16x32_bf16 v[24:27], v[160:163], v[200:203], v[24:27]
	v_mfma_f32_16x16x32_bf16 v[12:15], v[144:147], v[208:211], v[12:15]
	v_mfma_f32_16x16x32_bf16 v[8:11], v[160:163], v[208:211], v[8:11]
	v_mfma_f32_16x16x32_bf16 v[60:63], v[156:159], v[188:191], v[60:63]
	v_mfma_f32_16x16x32_bf16 v[56:59], v[164:167], v[188:191], v[56:59]
	v_mfma_f32_16x16x32_bf16 v[44:47], v[156:159], v[196:199], v[44:47]
	v_mfma_f32_16x16x32_bf16 v[40:43], v[164:167], v[196:199], v[40:43]
	v_mfma_f32_16x16x32_bf16 v[28:31], v[156:159], v[204:207], v[28:31]
	v_mfma_f32_16x16x32_bf16 v[24:27], v[164:167], v[204:207], v[24:27]
	v_mfma_f32_16x16x32_bf16 v[12:15], v[156:159], v[212:215], v[12:15]
	v_mfma_f32_16x16x32_bf16 v[8:11], v[164:167], v[212:215], v[8:11]
	v_mfma_f32_16x16x32_bf16 v[52:55], v[168:171], v[184:187], v[52:55]
	v_mfma_f32_16x16x32_bf16 v[48:51], v[176:179], v[184:187], v[48:51]
	v_mfma_f32_16x16x32_bf16 v[36:39], v[168:171], v[192:195], v[36:39]
	v_mfma_f32_16x16x32_bf16 v[32:35], v[176:179], v[192:195], v[32:35]
	v_mfma_f32_16x16x32_bf16 v[20:23], v[168:171], v[200:203], v[20:23]
	v_mfma_f32_16x16x32_bf16 v[16:19], v[176:179], v[200:203], v[16:19]
	v_mfma_f32_16x16x32_bf16 v[4:7], v[168:171], v[208:211], v[4:7]
	v_mfma_f32_16x16x32_bf16 v[0:3], v[176:179], v[208:211], v[0:3]
	v_mfma_f32_16x16x32_bf16 v[52:55], v[172:175], v[188:191], v[52:55]
	v_mfma_f32_16x16x32_bf16 v[48:51], v[180:183], v[188:191], v[48:51]
	v_mfma_f32_16x16x32_bf16 v[36:39], v[172:175], v[196:199], v[36:39]
	v_mfma_f32_16x16x32_bf16 v[32:35], v[180:183], v[196:199], v[32:35]
	v_mfma_f32_16x16x32_bf16 v[20:23], v[172:175], v[204:207], v[20:23]
	v_mfma_f32_16x16x32_bf16 v[16:19], v[180:183], v[204:207], v[16:19]
	v_mfma_f32_16x16x32_bf16 v[4:7], v[172:175], v[212:215], v[4:7]
	v_mfma_f32_16x16x32_bf16 v[0:3], v[180:183], v[212:215], v[0:3]
	s_barrier
	s_add_u32 s98, s30, 0x100000
	s_addc_u32 s99, s31, 0
	ds_read_b128 v[144:147], v153 offset:32768
	ds_read_b128 v[156:159], v153 offset:33792
	ds_read_b128 v[160:163], v153 offset:34816
	ds_read_b128 v[164:167], v153 offset:35840
	ds_read_b128 v[168:171], v154 offset:32768
	ds_read_b128 v[172:175], v154 offset:33792
	ds_read_b128 v[176:179], v154 offset:34816
	ds_read_b128 v[180:183], v154 offset:35840
	ds_read_b128 v[184:187], v155 offset:32768
	ds_read_b128 v[188:191], v155 offset:33792
	ds_read_b128 v[192:195], v155 offset:34816
	ds_read_b128 v[196:199], v155 offset:35840
	ds_read_b128 v[200:203], v155 offset:36864
	ds_read_b128 v[204:207], v155 offset:37888
	s_add_i32 m0, s29, 0x4000
	ds_read_b128 v[208:211], v155 offset:38912
	global_load_lds_dwordx4 v128, s[98:99]
	s_add_i32 m0, s29, 0x6000
	ds_read_b128 v[212:215], v155 offset:39936
	global_load_lds_dwordx4 v132, s[98:99]
	s_waitcnt vmcnt(8) lgkmcnt(0)
	s_barrier
	v_mfma_f32_16x16x32_bf16 v[124:127], v[144:147], v[184:187], v[124:127]
	v_mfma_f32_16x16x32_bf16 v[120:123], v[160:163], v[184:187], v[120:123]
	v_mfma_f32_16x16x32_bf16 v[108:111], v[144:147], v[192:195], v[108:111]
	v_mfma_f32_16x16x32_bf16 v[104:107], v[160:163], v[192:195], v[104:107]
	v_mfma_f32_16x16x32_bf16 v[92:95], v[144:147], v[200:203], v[92:95]
	v_mfma_f32_16x16x32_bf16 v[88:91], v[160:163], v[200:203], v[88:91]
	v_mfma_f32_16x16x32_bf16 v[76:79], v[144:147], v[208:211], v[76:79]
	v_mfma_f32_16x16x32_bf16 v[72:75], v[160:163], v[208:211], v[72:75]
	v_mfma_f32_16x16x32_bf16 v[124:127], v[156:159], v[188:191], v[124:127]
	v_mfma_f32_16x16x32_bf16 v[120:123], v[164:167], v[188:191], v[120:123]
	v_mfma_f32_16x16x32_bf16 v[108:111], v[156:159], v[196:199], v[108:111]
	v_mfma_f32_16x16x32_bf16 v[104:107], v[164:167], v[196:199], v[104:107]
	v_mfma_f32_16x16x32_bf16 v[92:95], v[156:159], v[204:207], v[92:95]
	v_mfma_f32_16x16x32_bf16 v[88:91], v[164:167], v[204:207], v[88:91]
	v_mfma_f32_16x16x32_bf16 v[76:79], v[156:159], v[212:215], v[76:79]
	v_mfma_f32_16x16x32_bf16 v[72:75], v[164:167], v[212:215], v[72:75]
	v_mfma_f32_16x16x32_bf16 v[116:119], v[168:171], v[184:187], v[116:119]
	v_mfma_f32_16x16x32_bf16 v[112:115], v[176:179], v[184:187], v[112:115]
	v_mfma_f32_16x16x32_bf16 v[100:103], v[168:171], v[192:195], v[100:103]
	v_mfma_f32_16x16x32_bf16 v[96:99], v[176:179], v[192:195], v[96:99]
	v_mfma_f32_16x16x32_bf16 v[84:87], v[168:171], v[200:203], v[84:87]
	v_mfma_f32_16x16x32_bf16 v[80:83], v[176:179], v[200:203], v[80:83]
	v_mfma_f32_16x16x32_bf16 v[68:71], v[168:171], v[208:211], v[68:71]
	v_mfma_f32_16x16x32_bf16 v[64:67], v[176:179], v[208:211], v[64:67]
	v_mfma_f32_16x16x32_bf16 v[116:119], v[172:175], v[188:191], v[116:119]
	v_mfma_f32_16x16x32_bf16 v[112:115], v[180:183], v[188:191], v[112:115]
	v_mfma_f32_16x16x32_bf16 v[100:103], v[172:175], v[196:199], v[100:103]
	v_mfma_f32_16x16x32_bf16 v[96:99], v[180:183], v[196:199], v[96:99]
	v_mfma_f32_16x16x32_bf16 v[84:87], v[172:175], v[204:207], v[84:87]
	v_mfma_f32_16x16x32_bf16 v[80:83], v[180:183], v[204:207], v[80:83]
	v_mfma_f32_16x16x32_bf16 v[68:71], v[172:175], v[212:215], v[68:71]
	v_mfma_f32_16x16x32_bf16 v[64:67], v[180:183], v[212:215], v[64:67]
	s_barrier
	s_add_u32 s100, s74, 0x80
	s_addc_u32 s101, s75, 0
	s_add_u32 s42, s74, 0x100080
	s_addc_u32 s43, s75, 0
	s_add_u32 s98, s30, 0x80
	s_addc_u32 s99, s31, 0
	ds_read_b128 v[184:187], v155 offset:49152
	ds_read_b128 v[188:191], v155 offset:50176
	s_add_i32 m0, s29, 0x18000
	ds_read_b128 v[192:195], v155 offset:51200
	global_load_lds_dwordx4 v130, s[100:101]
	s_add_i32 m0, s29, 0x1a000
	ds_read_b128 v[196:199], v155 offset:52224
	global_load_lds_dwordx4 v134, s[100:101]
	s_add_i32 m0, s29, 0x1c000
	ds_read_b128 v[200:203], v155 offset:53248
	global_load_lds_dwordx4 v130, s[42:43]
	s_add_i32 m0, s29, 0x1e000
	ds_read_b128 v[204:207], v155 offset:54272
	global_load_lds_dwordx4 v134, s[42:43]
	s_add_i32 m0, s29, 0x8000
	ds_read_b128 v[208:211], v155 offset:55296
	global_load_lds_dwordx4 v128, s[98:99]
	s_add_i32 m0, s29, 0xa000
	ds_read_b128 v[212:215], v155 offset:56320
	global_load_lds_dwordx4 v132, s[98:99]
	s_waitcnt vmcnt(8) lgkmcnt(0)
	s_barrier
	v_mfma_f32_16x16x32_bf16 v[60:63], v[144:147], v[184:187], v[60:63]
	v_mfma_f32_16x16x32_bf16 v[56:59], v[160:163], v[184:187], v[56:59]
	v_mfma_f32_16x16x32_bf16 v[44:47], v[144:147], v[192:195], v[44:47]
	v_mfma_f32_16x16x32_bf16 v[40:43], v[160:163], v[192:195], v[40:43]
	v_mfma_f32_16x16x32_bf16 v[28:31], v[144:147], v[200:203], v[28:31]
	v_mfma_f32_16x16x32_bf16 v[24:27], v[160:163], v[200:203], v[24:27]
	v_mfma_f32_16x16x32_bf16 v[12:15], v[144:147], v[208:211], v[12:15]
	v_mfma_f32_16x16x32_bf16 v[8:11], v[160:163], v[208:211], v[8:11]
	v_mfma_f32_16x16x32_bf16 v[60:63], v[156:159], v[188:191], v[60:63]
	v_mfma_f32_16x16x32_bf16 v[56:59], v[164:167], v[188:191], v[56:59]
	v_mfma_f32_16x16x32_bf16 v[44:47], v[156:159], v[196:199], v[44:47]
	v_mfma_f32_16x16x32_bf16 v[40:43], v[164:167], v[196:199], v[40:43]
	v_mfma_f32_16x16x32_bf16 v[28:31], v[156:159], v[204:207], v[28:31]
	v_mfma_f32_16x16x32_bf16 v[24:27], v[164:167], v[204:207], v[24:27]
	v_mfma_f32_16x16x32_bf16 v[12:15], v[156:159], v[212:215], v[12:15]
	v_mfma_f32_16x16x32_bf16 v[8:11], v[164:167], v[212:215], v[8:11]
	v_mfma_f32_16x16x32_bf16 v[52:55], v[168:171], v[184:187], v[52:55]
	v_mfma_f32_16x16x32_bf16 v[48:51], v[176:179], v[184:187], v[48:51]
	v_mfma_f32_16x16x32_bf16 v[36:39], v[168:171], v[192:195], v[36:39]
	v_mfma_f32_16x16x32_bf16 v[32:35], v[176:179], v[192:195], v[32:35]
	v_mfma_f32_16x16x32_bf16 v[20:23], v[168:171], v[200:203], v[20:23]
	v_mfma_f32_16x16x32_bf16 v[16:19], v[176:179], v[200:203], v[16:19]
	v_mfma_f32_16x16x32_bf16 v[4:7], v[168:171], v[208:211], v[4:7]
	v_mfma_f32_16x16x32_bf16 v[0:3], v[176:179], v[208:211], v[0:3]
	v_mfma_f32_16x16x32_bf16 v[52:55], v[172:175], v[188:191], v[52:55]
	v_mfma_f32_16x16x32_bf16 v[48:51], v[180:183], v[188:191], v[48:51]
	v_mfma_f32_16x16x32_bf16 v[36:39], v[172:175], v[196:199], v[36:39]
	v_mfma_f32_16x16x32_bf16 v[32:35], v[180:183], v[196:199], v[32:35]
	v_mfma_f32_16x16x32_bf16 v[20:23], v[172:175], v[204:207], v[20:23]
	v_mfma_f32_16x16x32_bf16 v[16:19], v[180:183], v[204:207], v[16:19]
	v_mfma_f32_16x16x32_bf16 v[4:7], v[172:175], v[212:215], v[4:7]
	v_mfma_f32_16x16x32_bf16 v[0:3], v[180:183], v[212:215], v[0:3]
	s_barrier
	s_add_i32 s41, s41, 2
	s_add_u32 s72, s72, 0x100
	s_addc_u32 s73, s73, 0
	s_add_u32 s39, s39, 0x100
	s_addc_u32 s40, s40, 0
	s_cmp_gt_u32 s41, 61
	s_cbranch_scc0 .LBB0_182
	s_and_b64 vcc, exec, s[6:7]
	s_cbranch_vccz .LBB0_185
	s_barrier

.LBB0_401:
	ds_read_b128 v[142:145], v169 offset:0
	ds_read_b128 v[146:149], v169 offset:1024
	ds_read_b128 v[150:153], v169 offset:2048
	ds_read_b128 v[154:157], v169 offset:3072
	ds_read_b128 v[158:161], v170 offset:0
	ds_read_b128 v[162:165], v170 offset:1024
	ds_read_b128 v[172:175], v170 offset:2048
	ds_read_b128 v[176:179], v170 offset:3072
	s_add_i32 s38, s30, 2
	s_add_u32 s46, s44, 0x100
	s_addc_u32 s47, s45, 0
	s_cmp_eq_u32 s17, s30
	s_cselect_b32 s30, s34, s46
	s_cselect_b32 s31, s35, s47
	s_cselect_b32 s53, s41, s37
	s_cselect_b32 s52, s40, s36
	ds_read_b128 v[180:183], v171 offset:0
	ds_read_b128 v[184:187], v171 offset:1024
	ds_read_b128 v[188:191], v171 offset:2048
	ds_read_b128 v[192:195], v171 offset:3072
	ds_read_b128 v[196:199], v171 offset:4096
	ds_read_b128 v[200:203], v171 offset:5120
	s_add_i32 m0, s60, 0xc000
	ds_read_b128 v[204:207], v171 offset:6144
	global_load_lds_dwordx4 v136, s[44:45]
	s_add_i32 m0, s60, 0xe000
	ds_read_b128 v[208:211], v171 offset:7168
	global_load_lds_dwordx4 v138, s[44:45]
	s_waitcnt vmcnt(8) lgkmcnt(0)
	s_barrier
	v_mfma_f32_16x16x32_bf16 v[124:127], v[142:145], v[180:183], v[124:127]
	v_mfma_f32_16x16x32_bf16 v[120:123], v[150:153], v[180:183], v[120:123]
	v_mfma_f32_16x16x32_bf16 v[108:111], v[142:145], v[188:191], v[108:111]
	v_mfma_f32_16x16x32_bf16 v[104:107], v[150:153], v[188:191], v[104:107]
	v_mfma_f32_16x16x32_bf16 v[92:95], v[142:145], v[196:199], v[92:95]
	v_mfma_f32_16x16x32_bf16 v[88:91], v[150:153], v[196:199], v[88:91]
	v_mfma_f32_16x16x32_bf16 v[76:79], v[142:145], v[204:207], v[76:79]
	v_mfma_f32_16x16x32_bf16 v[72:75], v[150:153], v[204:207], v[72:75]
	v_mfma_f32_16x16x32_bf16 v[124:127], v[146:149], v[184:187], v[124:127]
	v_mfma_f32_16x16x32_bf16 v[120:123], v[154:157], v[184:187], v[120:123]
	v_mfma_f32_16x16x32_bf16 v[108:111], v[146:149], v[192:195], v[108:111]
	v_mfma_f32_16x16x32_bf16 v[104:107], v[154:157], v[192:195], v[104:107]
	v_mfma_f32_16x16x32_bf16 v[92:95], v[146:149], v[200:203], v[92:95]
	v_mfma_f32_16x16x32_bf16 v[88:91], v[154:157], v[200:203], v[88:91]
	v_mfma_f32_16x16x32_bf16 v[76:79], v[146:149], v[208:211], v[76:79]
	v_mfma_f32_16x16x32_bf16 v[72:75], v[154:157], v[208:211], v[72:75]
	v_mfma_f32_16x16x32_bf16 v[116:119], v[158:161], v[180:183], v[116:119]
	v_mfma_f32_16x16x32_bf16 v[112:115], v[172:175], v[180:183], v[112:115]
	v_mfma_f32_16x16x32_bf16 v[100:103], v[158:161], v[188:191], v[100:103]
	v_mfma_f32_16x16x32_bf16 v[96:99], v[172:175], v[188:191], v[96:99]
	v_mfma_f32_16x16x32_bf16 v[84:87], v[158:161], v[196:199], v[84:87]
	v_mfma_f32_16x16x32_bf16 v[80:83], v[172:175], v[196:199], v[80:83]
	v_mfma_f32_16x16x32_bf16 v[68:71], v[158:161], v[204:207], v[68:71]
	v_mfma_f32_16x16x32_bf16 v[64:67], v[172:175], v[204:207], v[64:67]
	v_mfma_f32_16x16x32_bf16 v[116:119], v[162:165], v[184:187], v[116:119]
	v_mfma_f32_16x16x32_bf16 v[112:115], v[176:179], v[184:187], v[112:115]
	v_mfma_f32_16x16x32_bf16 v[100:103], v[162:165], v[192:195], v[100:103]
	v_mfma_f32_16x16x32_bf16 v[96:99], v[176:179], v[192:195], v[96:99]
	v_mfma_f32_16x16x32_bf16 v[84:87], v[162:165], v[200:203], v[84:87]
	v_mfma_f32_16x16x32_bf16 v[80:83], v[176:179], v[200:203], v[80:83]
	v_mfma_f32_16x16x32_bf16 v[68:71], v[162:165], v[208:211], v[68:71]
	v_mfma_f32_16x16x32_bf16 v[64:67], v[176:179], v[208:211], v[64:67]
	s_barrier
	s_add_u32 s42, s52, 0x2b0000
	s_addc_u32 s43, s53, 0
	ds_read_b128 v[180:183], v171 offset:16384
	ds_read_b128 v[184:187], v171 offset:17408
	s_add_i32 m0, s60, 0x10000
	ds_read_b128 v[188:191], v171 offset:18432
	global_load_lds_dwordx4 v130, s[52:53]
	s_add_i32 m0, s60, 0x12000
	ds_read_b128 v[192:195], v171 offset:19456
	global_load_lds_dwordx4 v134, s[52:53]
	s_add_i32 m0, s60, 0x14000
	ds_read_b128 v[196:199], v171 offset:20480
	global_load_lds_dwordx4 v130, s[42:43]
	s_add_i32 m0, s60, 0x16000
	ds_read_b128 v[200:203], v171 offset:21504
	global_load_lds_dwordx4 v134, s[42:43]
	s_add_i32 m0, s60, 0x0
	ds_read_b128 v[204:207], v171 offset:22528
	global_load_lds_dwordx4 v128, s[30:31]
	s_add_i32 m0, s60, 0x2000
	ds_read_b128 v[208:211], v171 offset:23552
	global_load_lds_dwordx4 v132, s[30:31]
	s_waitcnt vmcnt(8) lgkmcnt(0)
	s_barrier
	v_mfma_f32_16x16x32_bf16 v[60:63], v[142:145], v[180:183], v[60:63]
	v_mfma_f32_16x16x32_bf16 v[56:59], v[150:153], v[180:183], v[56:59]
	v_mfma_f32_16x16x32_bf16 v[44:47], v[142:145], v[188:191], v[44:47]
	v_mfma_f32_16x16x32_bf16 v[40:43], v[150:153], v[188:191], v[40:43]
	v_mfma_f32_16x16x32_bf16 v[28:31], v[142:145], v[196:199], v[28:31]
	v_mfma_f32_16x16x32_bf16 v[24:27], v[150:153], v[196:199], v[24:27]
	v_mfma_f32_16x16x32_bf16 v[12:15], v[142:145], v[204:207], v[12:15]
	v_mfma_f32_16x16x32_bf16 v[8:11], v[150:153], v[204:207], v[8:11]
	v_mfma_f32_16x16x32_bf16 v[60:63], v[146:149], v[184:187], v[60:63]
	v_mfma_f32_16x16x32_bf16 v[56:59], v[154:157], v[184:187], v[56:59]
	v_mfma_f32_16x16x32_bf16 v[44:47], v[146:149], v[192:195], v[44:47]
	v_mfma_f32_16x16x32_bf16 v[40:43], v[154:157], v[192:195], v[40:43]
	v_mfma_f32_16x16x32_bf16 v[28:31], v[146:149], v[200:203], v[28:31]
	v_mfma_f32_16x16x32_bf16 v[24:27], v[154:157], v[200:203], v[24:27]
	v_mfma_f32_16x16x32_bf16 v[12:15], v[146:149], v[208:211], v[12:15]
	v_mfma_f32_16x16x32_bf16 v[8:11], v[154:157], v[208:211], v[8:11]
	v_mfma_f32_16x16x32_bf16 v[52:55], v[158:161], v[180:183], v[52:55]
	v_mfma_f32_16x16x32_bf16 v[48:51], v[172:175], v[180:183], v[48:51]
	v_mfma_f32_16x16x32_bf16 v[36:39], v[158:161], v[188:191], v[36:39]
	v_mfma_f32_16x16x32_bf16 v[32:35], v[172:175], v[188:191], v[32:35]
	v_mfma_f32_16x16x32_bf16 v[20:23], v[158:161], v[196:199], v[20:23]
	v_mfma_f32_16x16x32_bf16 v[16:19], v[172:175], v[196:199], v[16:19]
	v_mfma_f32_16x16x32_bf16 v[4:7], v[158:161], v[204:207], v[4:7]
	v_mfma_f32_16x16x32_bf16 v[0:3], v[172:175], v[204:207], v[0:3]
	v_mfma_f32_16x16x32_bf16 v[52:55], v[162:165], v[184:187], v[52:55]
	v_mfma_f32_16x16x32_bf16 v[48:51], v[176:179], v[184:187], v[48:51]
	v_mfma_f32_16x16x32_bf16 v[36:39], v[162:165], v[192:195], v[36:39]
	v_mfma_f32_16x16x32_bf16 v[32:35], v[176:179], v[192:195], v[32:35]
	v_mfma_f32_16x16x32_bf16 v[20:23], v[162:165], v[200:203], v[20:23]
	v_mfma_f32_16x16x32_bf16 v[16:19], v[176:179], v[200:203], v[16:19]
	v_mfma_f32_16x16x32_bf16 v[4:7], v[162:165], v[208:211], v[4:7]
	v_mfma_f32_16x16x32_bf16 v[0:3], v[176:179], v[208:211], v[0:3]
	s_barrier
	s_add_u32 s98, s30, 0x2b0000
	s_addc_u32 s99, s31, 0
	ds_read_b128 v[142:145], v169 offset:32768
	ds_read_b128 v[146:149], v169 offset:33792
	ds_read_b128 v[150:153], v169 offset:34816
	ds_read_b128 v[154:157], v169 offset:35840
	ds_read_b128 v[158:161], v170 offset:32768
	ds_read_b128 v[162:165], v170 offset:33792
	ds_read_b128 v[172:175], v170 offset:34816
	ds_read_b128 v[176:179], v170 offset:35840
	ds_read_b128 v[180:183], v171 offset:32768
	ds_read_b128 v[184:187], v171 offset:33792
	ds_read_b128 v[188:191], v171 offset:34816
	ds_read_b128 v[192:195], v171 offset:35840
	ds_read_b128 v[196:199], v171 offset:36864
	ds_read_b128 v[200:203], v171 offset:37888
	s_add_i32 m0, s60, 0x4000
	ds_read_b128 v[204:207], v171 offset:38912
	global_load_lds_dwordx4 v128, s[98:99]
	s_add_i32 m0, s60, 0x6000
	ds_read_b128 v[208:211], v171 offset:39936
	global_load_lds_dwordx4 v132, s[98:99]
	s_waitcnt vmcnt(8) lgkmcnt(0)
	s_barrier
	v_mfma_f32_16x16x32_bf16 v[124:127], v[142:145], v[180:183], v[124:127]
	v_mfma_f32_16x16x32_bf16 v[120:123], v[150:153], v[180:183], v[120:123]
	v_mfma_f32_16x16x32_bf16 v[108:111], v[142:145], v[188:191], v[108:111]
	v_mfma_f32_16x16x32_bf16 v[104:107], v[150:153], v[188:191], v[104:107]
	v_mfma_f32_16x16x32_bf16 v[92:95], v[142:145], v[196:199], v[92:95]
	v_mfma_f32_16x16x32_bf16 v[88:91], v[150:153], v[196:199], v[88:91]
	v_mfma_f32_16x16x32_bf16 v[76:79], v[142:145], v[204:207], v[76:79]
	v_mfma_f32_16x16x32_bf16 v[72:75], v[150:153], v[204:207], v[72:75]
	v_mfma_f32_16x16x32_bf16 v[124:127], v[146:149], v[184:187], v[124:127]
	v_mfma_f32_16x16x32_bf16 v[120:123], v[154:157], v[184:187], v[120:123]
	v_mfma_f32_16x16x32_bf16 v[108:111], v[146:149], v[192:195], v[108:111]
	v_mfma_f32_16x16x32_bf16 v[104:107], v[154:157], v[192:195], v[104:107]
	v_mfma_f32_16x16x32_bf16 v[92:95], v[146:149], v[200:203], v[92:95]
	v_mfma_f32_16x16x32_bf16 v[88:91], v[154:157], v[200:203], v[88:91]
	v_mfma_f32_16x16x32_bf16 v[76:79], v[146:149], v[208:211], v[76:79]
	v_mfma_f32_16x16x32_bf16 v[72:75], v[154:157], v[208:211], v[72:75]
	v_mfma_f32_16x16x32_bf16 v[116:119], v[158:161], v[180:183], v[116:119]
	v_mfma_f32_16x16x32_bf16 v[112:115], v[172:175], v[180:183], v[112:115]
	v_mfma_f32_16x16x32_bf16 v[100:103], v[158:161], v[188:191], v[100:103]
	v_mfma_f32_16x16x32_bf16 v[96:99], v[172:175], v[188:191], v[96:99]
	v_mfma_f32_16x16x32_bf16 v[84:87], v[158:161], v[196:199], v[84:87]
	v_mfma_f32_16x16x32_bf16 v[80:83], v[172:175], v[196:199], v[80:83]
	v_mfma_f32_16x16x32_bf16 v[68:71], v[158:161], v[204:207], v[68:71]
	v_mfma_f32_16x16x32_bf16 v[64:67], v[172:175], v[204:207], v[64:67]
	v_mfma_f32_16x16x32_bf16 v[116:119], v[162:165], v[184:187], v[116:119]
	v_mfma_f32_16x16x32_bf16 v[112:115], v[176:179], v[184:187], v[112:115]
	v_mfma_f32_16x16x32_bf16 v[100:103], v[162:165], v[192:195], v[100:103]
	v_mfma_f32_16x16x32_bf16 v[96:99], v[176:179], v[192:195], v[96:99]
	v_mfma_f32_16x16x32_bf16 v[84:87], v[162:165], v[200:203], v[84:87]
	v_mfma_f32_16x16x32_bf16 v[80:83], v[176:179], v[200:203], v[80:83]
	v_mfma_f32_16x16x32_bf16 v[68:71], v[162:165], v[208:211], v[68:71]
	v_mfma_f32_16x16x32_bf16 v[64:67], v[176:179], v[208:211], v[64:67]
	s_barrier
	s_add_u32 s100, s52, 0x80
	s_addc_u32 s101, s53, 0
	s_add_u32 s42, s52, 0x2b0080
	s_addc_u32 s43, s53, 0
	s_add_u32 s98, s30, 0x80
	s_addc_u32 s99, s31, 0
	ds_read_b128 v[180:183], v171 offset:49152
	ds_read_b128 v[184:187], v171 offset:50176
	s_add_i32 m0, s60, 0x18000
	ds_read_b128 v[188:191], v171 offset:51200
	global_load_lds_dwordx4 v130, s[100:101]
	s_add_i32 m0, s60, 0x1a000
	ds_read_b128 v[192:195], v171 offset:52224
	global_load_lds_dwordx4 v134, s[100:101]
	s_add_i32 m0, s60, 0x1c000
	ds_read_b128 v[196:199], v171 offset:53248
	global_load_lds_dwordx4 v130, s[42:43]
	s_add_i32 m0, s60, 0x1e000
	ds_read_b128 v[200:203], v171 offset:54272
	global_load_lds_dwordx4 v134, s[42:43]
	s_add_i32 m0, s60, 0x8000
	ds_read_b128 v[204:207], v171 offset:55296
	global_load_lds_dwordx4 v128, s[98:99]
	s_add_i32 m0, s60, 0xa000
	ds_read_b128 v[208:211], v171 offset:56320
	global_load_lds_dwordx4 v132, s[98:99]
	s_waitcnt vmcnt(8) lgkmcnt(0)
	s_barrier
	v_mfma_f32_16x16x32_bf16 v[60:63], v[142:145], v[180:183], v[60:63]
	v_mfma_f32_16x16x32_bf16 v[56:59], v[150:153], v[180:183], v[56:59]
	v_mfma_f32_16x16x32_bf16 v[44:47], v[142:145], v[188:191], v[44:47]
	v_mfma_f32_16x16x32_bf16 v[40:43], v[150:153], v[188:191], v[40:43]
	v_mfma_f32_16x16x32_bf16 v[28:31], v[142:145], v[196:199], v[28:31]
	v_mfma_f32_16x16x32_bf16 v[24:27], v[150:153], v[196:199], v[24:27]
	v_mfma_f32_16x16x32_bf16 v[12:15], v[142:145], v[204:207], v[12:15]
	v_mfma_f32_16x16x32_bf16 v[8:11], v[150:153], v[204:207], v[8:11]
	v_mfma_f32_16x16x32_bf16 v[60:63], v[146:149], v[184:187], v[60:63]
	v_mfma_f32_16x16x32_bf16 v[56:59], v[154:157], v[184:187], v[56:59]
	v_mfma_f32_16x16x32_bf16 v[44:47], v[146:149], v[192:195], v[44:47]
	v_mfma_f32_16x16x32_bf16 v[40:43], v[154:157], v[192:195], v[40:43]
	v_mfma_f32_16x16x32_bf16 v[28:31], v[146:149], v[200:203], v[28:31]
	v_mfma_f32_16x16x32_bf16 v[24:27], v[154:157], v[200:203], v[24:27]
	v_mfma_f32_16x16x32_bf16 v[12:15], v[146:149], v[208:211], v[12:15]
	v_mfma_f32_16x16x32_bf16 v[8:11], v[154:157], v[208:211], v[8:11]
	v_mfma_f32_16x16x32_bf16 v[52:55], v[158:161], v[180:183], v[52:55]
	v_mfma_f32_16x16x32_bf16 v[48:51], v[172:175], v[180:183], v[48:51]
	v_mfma_f32_16x16x32_bf16 v[36:39], v[158:161], v[188:191], v[36:39]
	v_mfma_f32_16x16x32_bf16 v[32:35], v[172:175], v[188:191], v[32:35]
	v_mfma_f32_16x16x32_bf16 v[20:23], v[158:161], v[196:199], v[20:23]
	v_mfma_f32_16x16x32_bf16 v[16:19], v[172:175], v[196:199], v[16:19]
	v_mfma_f32_16x16x32_bf16 v[4:7], v[158:161], v[204:207], v[4:7]
	v_mfma_f32_16x16x32_bf16 v[0:3], v[172:175], v[204:207], v[0:3]
	v_mfma_f32_16x16x32_bf16 v[52:55], v[162:165], v[184:187], v[52:55]
	v_mfma_f32_16x16x32_bf16 v[48:51], v[176:179], v[184:187], v[48:51]
	v_mfma_f32_16x16x32_bf16 v[36:39], v[162:165], v[192:195], v[36:39]
	v_mfma_f32_16x16x32_bf16 v[32:35], v[176:179], v[192:195], v[32:35]
	v_mfma_f32_16x16x32_bf16 v[20:23], v[162:165], v[200:203], v[20:23]
	v_mfma_f32_16x16x32_bf16 v[16:19], v[176:179], v[200:203], v[16:19]
	v_mfma_f32_16x16x32_bf16 v[4:7], v[162:165], v[208:211], v[4:7]
	v_mfma_f32_16x16x32_bf16 v[0:3], v[176:179], v[208:211], v[0:3]
	s_barrier
	s_add_u32 s36, s36, 0x100
	s_addc_u32 s37, s37, 0
	s_cmp_ge_i32 s38, s87
	s_mov_b64 s[44:45], s[46:47]
	s_mov_b32 s30, s38
	s_cbranch_scc0 .LBB0_401
	s_and_b64 vcc, exec, s[12:13]
	s_cbranch_vccz .LBB0_404

.LBB0_1299:
	ds_read_b128 v[144:147], v153 offset:0
	ds_read_b128 v[156:159], v153 offset:1024
	ds_read_b128 v[160:163], v153 offset:2048
	ds_read_b128 v[164:167], v153 offset:3072
	ds_read_b128 v[168:171], v154 offset:0
	ds_read_b128 v[172:175], v154 offset:1024
	ds_read_b128 v[176:179], v154 offset:2048
	ds_read_b128 v[180:183], v154 offset:3072
	s_add_u32 s36, s34, 0xfff00080
	s_addc_u32 s37, s35, -1
	s_cmp_eq_u32 s57, 60
	s_cselect_b32 s39, s13, s37
	s_cselect_b32 s38, s53, s36
	s_cselect_b32 s37, s11, s56
	s_cselect_b32 s36, s54, s55
	ds_read_b128 v[184:187], v155 offset:0
	ds_read_b128 v[188:191], v155 offset:1024
	ds_read_b128 v[192:195], v155 offset:2048
	ds_read_b128 v[196:199], v155 offset:3072
	ds_read_b128 v[202:205], v155 offset:4096
	ds_read_b128 v[206:209], v155 offset:5120
	s_add_i32 m0, s31, 0xc000
	ds_read_b128 v[210:213], v155 offset:6144
	global_load_lds_dwordx4 v136, s[34:35]
	s_add_i32 m0, s31, 0xe000
	ds_read_b128 v[214:217], v155 offset:7168
	global_load_lds_dwordx4 v138, s[34:35]
	s_waitcnt vmcnt(8) lgkmcnt(0)
	s_barrier
	v_mfma_f32_16x16x32_bf16 v[124:127], v[144:147], v[184:187], v[124:127]
	v_mfma_f32_16x16x32_bf16 v[120:123], v[160:163], v[184:187], v[120:123]
	v_mfma_f32_16x16x32_bf16 v[108:111], v[144:147], v[192:195], v[108:111]
	v_mfma_f32_16x16x32_bf16 v[104:107], v[160:163], v[192:195], v[104:107]
	v_mfma_f32_16x16x32_bf16 v[92:95], v[144:147], v[202:205], v[92:95]
	v_mfma_f32_16x16x32_bf16 v[88:91], v[160:163], v[202:205], v[88:91]
	v_mfma_f32_16x16x32_bf16 v[76:79], v[144:147], v[210:213], v[76:79]
	v_mfma_f32_16x16x32_bf16 v[72:75], v[160:163], v[210:213], v[72:75]
	v_mfma_f32_16x16x32_bf16 v[124:127], v[156:159], v[188:191], v[124:127]
	v_mfma_f32_16x16x32_bf16 v[120:123], v[164:167], v[188:191], v[120:123]
	v_mfma_f32_16x16x32_bf16 v[108:111], v[156:159], v[196:199], v[108:111]
	v_mfma_f32_16x16x32_bf16 v[104:107], v[164:167], v[196:199], v[104:107]
	v_mfma_f32_16x16x32_bf16 v[92:95], v[156:159], v[206:209], v[92:95]
	v_mfma_f32_16x16x32_bf16 v[88:91], v[164:167], v[206:209], v[88:91]
	v_mfma_f32_16x16x32_bf16 v[76:79], v[156:159], v[214:217], v[76:79]
	v_mfma_f32_16x16x32_bf16 v[72:75], v[164:167], v[214:217], v[72:75]
	v_mfma_f32_16x16x32_bf16 v[116:119], v[168:171], v[184:187], v[116:119]
	v_mfma_f32_16x16x32_bf16 v[112:115], v[176:179], v[184:187], v[112:115]
	v_mfma_f32_16x16x32_bf16 v[100:103], v[168:171], v[192:195], v[100:103]
	v_mfma_f32_16x16x32_bf16 v[96:99], v[176:179], v[192:195], v[96:99]
	v_mfma_f32_16x16x32_bf16 v[84:87], v[168:171], v[202:205], v[84:87]
	v_mfma_f32_16x16x32_bf16 v[80:83], v[176:179], v[202:205], v[80:83]
	v_mfma_f32_16x16x32_bf16 v[68:71], v[168:171], v[210:213], v[68:71]
	v_mfma_f32_16x16x32_bf16 v[64:67], v[176:179], v[210:213], v[64:67]
	v_mfma_f32_16x16x32_bf16 v[116:119], v[172:175], v[188:191], v[116:119]
	v_mfma_f32_16x16x32_bf16 v[112:115], v[180:183], v[188:191], v[112:115]
	v_mfma_f32_16x16x32_bf16 v[100:103], v[172:175], v[196:199], v[100:103]
	v_mfma_f32_16x16x32_bf16 v[96:99], v[180:183], v[196:199], v[96:99]
	v_mfma_f32_16x16x32_bf16 v[84:87], v[172:175], v[206:209], v[84:87]
	v_mfma_f32_16x16x32_bf16 v[80:83], v[180:183], v[206:209], v[80:83]
	v_mfma_f32_16x16x32_bf16 v[68:71], v[172:175], v[214:217], v[68:71]
	v_mfma_f32_16x16x32_bf16 v[64:67], v[180:183], v[214:217], v[64:67]
	s_barrier
	s_add_u32 s58, s36, 0x100000
	s_addc_u32 s59, s37, 0
	ds_read_b128 v[184:187], v155 offset:16384
	ds_read_b128 v[188:191], v155 offset:17408
	s_add_i32 m0, s31, 0x10000
	ds_read_b128 v[192:195], v155 offset:18432
	global_load_lds_dwordx4 v130, s[36:37]
	s_add_i32 m0, s31, 0x12000
	ds_read_b128 v[196:199], v155 offset:19456
	global_load_lds_dwordx4 v134, s[36:37]
	s_add_i32 m0, s31, 0x14000
	ds_read_b128 v[202:205], v155 offset:20480
	global_load_lds_dwordx4 v130, s[58:59]
	s_add_i32 m0, s31, 0x16000
	ds_read_b128 v[206:209], v155 offset:21504
	global_load_lds_dwordx4 v134, s[58:59]
	s_add_i32 m0, s31, 0x0
	ds_read_b128 v[210:213], v155 offset:22528
	global_load_lds_dwordx4 v128, s[38:39]
	s_add_i32 m0, s31, 0x2000
	ds_read_b128 v[214:217], v155 offset:23552
	global_load_lds_dwordx4 v132, s[38:39]
	s_waitcnt vmcnt(8) lgkmcnt(0)
	s_barrier
	v_mfma_f32_16x16x32_bf16 v[60:63], v[144:147], v[184:187], v[60:63]
	v_mfma_f32_16x16x32_bf16 v[56:59], v[160:163], v[184:187], v[56:59]
	v_mfma_f32_16x16x32_bf16 v[44:47], v[144:147], v[192:195], v[44:47]
	v_mfma_f32_16x16x32_bf16 v[40:43], v[160:163], v[192:195], v[40:43]
	v_mfma_f32_16x16x32_bf16 v[28:31], v[144:147], v[202:205], v[28:31]
	v_mfma_f32_16x16x32_bf16 v[24:27], v[160:163], v[202:205], v[24:27]
	v_mfma_f32_16x16x32_bf16 v[12:15], v[144:147], v[210:213], v[12:15]
	v_mfma_f32_16x16x32_bf16 v[8:11], v[160:163], v[210:213], v[8:11]
	v_mfma_f32_16x16x32_bf16 v[60:63], v[156:159], v[188:191], v[60:63]
	v_mfma_f32_16x16x32_bf16 v[56:59], v[164:167], v[188:191], v[56:59]
	v_mfma_f32_16x16x32_bf16 v[44:47], v[156:159], v[196:199], v[44:47]
	v_mfma_f32_16x16x32_bf16 v[40:43], v[164:167], v[196:199], v[40:43]
	v_mfma_f32_16x16x32_bf16 v[28:31], v[156:159], v[206:209], v[28:31]
	v_mfma_f32_16x16x32_bf16 v[24:27], v[164:167], v[206:209], v[24:27]
	v_mfma_f32_16x16x32_bf16 v[12:15], v[156:159], v[214:217], v[12:15]
	v_mfma_f32_16x16x32_bf16 v[8:11], v[164:167], v[214:217], v[8:11]
	v_mfma_f32_16x16x32_bf16 v[52:55], v[168:171], v[184:187], v[52:55]
	v_mfma_f32_16x16x32_bf16 v[48:51], v[176:179], v[184:187], v[48:51]
	v_mfma_f32_16x16x32_bf16 v[36:39], v[168:171], v[192:195], v[36:39]
	v_mfma_f32_16x16x32_bf16 v[32:35], v[176:179], v[192:195], v[32:35]
	v_mfma_f32_16x16x32_bf16 v[20:23], v[168:171], v[202:205], v[20:23]
	v_mfma_f32_16x16x32_bf16 v[16:19], v[176:179], v[202:205], v[16:19]
	v_mfma_f32_16x16x32_bf16 v[4:7], v[168:171], v[210:213], v[4:7]
	v_mfma_f32_16x16x32_bf16 v[0:3], v[176:179], v[210:213], v[0:3]
	v_mfma_f32_16x16x32_bf16 v[52:55], v[172:175], v[188:191], v[52:55]
	v_mfma_f32_16x16x32_bf16 v[48:51], v[180:183], v[188:191], v[48:51]
	v_mfma_f32_16x16x32_bf16 v[36:39], v[172:175], v[196:199], v[36:39]
	v_mfma_f32_16x16x32_bf16 v[32:35], v[180:183], v[196:199], v[32:35]
	v_mfma_f32_16x16x32_bf16 v[20:23], v[172:175], v[206:209], v[20:23]
	v_mfma_f32_16x16x32_bf16 v[16:19], v[180:183], v[206:209], v[16:19]
	v_mfma_f32_16x16x32_bf16 v[4:7], v[172:175], v[214:217], v[4:7]
	v_mfma_f32_16x16x32_bf16 v[0:3], v[180:183], v[214:217], v[0:3]
	s_barrier
	s_add_u32 s98, s38, 0x100000
	s_addc_u32 s99, s39, 0
	ds_read_b128 v[144:147], v153 offset:32768
	ds_read_b128 v[156:159], v153 offset:33792
	ds_read_b128 v[160:163], v153 offset:34816
	ds_read_b128 v[164:167], v153 offset:35840
	ds_read_b128 v[168:171], v154 offset:32768
	ds_read_b128 v[172:175], v154 offset:33792
	ds_read_b128 v[176:179], v154 offset:34816
	ds_read_b128 v[180:183], v154 offset:35840
	ds_read_b128 v[184:187], v155 offset:32768
	ds_read_b128 v[188:191], v155 offset:33792
	ds_read_b128 v[192:195], v155 offset:34816
	ds_read_b128 v[196:199], v155 offset:35840
	ds_read_b128 v[202:205], v155 offset:36864
	ds_read_b128 v[206:209], v155 offset:37888
	s_add_i32 m0, s31, 0x4000
	ds_read_b128 v[210:213], v155 offset:38912
	global_load_lds_dwordx4 v128, s[98:99]
	s_add_i32 m0, s31, 0x6000
	ds_read_b128 v[214:217], v155 offset:39936
	global_load_lds_dwordx4 v132, s[98:99]
	s_waitcnt vmcnt(8) lgkmcnt(0)
	s_barrier
	v_mfma_f32_16x16x32_bf16 v[124:127], v[144:147], v[184:187], v[124:127]
	v_mfma_f32_16x16x32_bf16 v[120:123], v[160:163], v[184:187], v[120:123]
	v_mfma_f32_16x16x32_bf16 v[108:111], v[144:147], v[192:195], v[108:111]
	v_mfma_f32_16x16x32_bf16 v[104:107], v[160:163], v[192:195], v[104:107]
	v_mfma_f32_16x16x32_bf16 v[92:95], v[144:147], v[202:205], v[92:95]
	v_mfma_f32_16x16x32_bf16 v[88:91], v[160:163], v[202:205], v[88:91]
	v_mfma_f32_16x16x32_bf16 v[76:79], v[144:147], v[210:213], v[76:79]
	v_mfma_f32_16x16x32_bf16 v[72:75], v[160:163], v[210:213], v[72:75]
	v_mfma_f32_16x16x32_bf16 v[124:127], v[156:159], v[188:191], v[124:127]
	v_mfma_f32_16x16x32_bf16 v[120:123], v[164:167], v[188:191], v[120:123]
	v_mfma_f32_16x16x32_bf16 v[108:111], v[156:159], v[196:199], v[108:111]
	v_mfma_f32_16x16x32_bf16 v[104:107], v[164:167], v[196:199], v[104:107]
	v_mfma_f32_16x16x32_bf16 v[92:95], v[156:159], v[206:209], v[92:95]
	v_mfma_f32_16x16x32_bf16 v[88:91], v[164:167], v[206:209], v[88:91]
	v_mfma_f32_16x16x32_bf16 v[76:79], v[156:159], v[214:217], v[76:79]
	v_mfma_f32_16x16x32_bf16 v[72:75], v[164:167], v[214:217], v[72:75]
	v_mfma_f32_16x16x32_bf16 v[116:119], v[168:171], v[184:187], v[116:119]
	v_mfma_f32_16x16x32_bf16 v[112:115], v[176:179], v[184:187], v[112:115]
	v_mfma_f32_16x16x32_bf16 v[100:103], v[168:171], v[192:195], v[100:103]
	v_mfma_f32_16x16x32_bf16 v[96:99], v[176:179], v[192:195], v[96:99]
	v_mfma_f32_16x16x32_bf16 v[84:87], v[168:171], v[202:205], v[84:87]
	v_mfma_f32_16x16x32_bf16 v[80:83], v[176:179], v[202:205], v[80:83]
	v_mfma_f32_16x16x32_bf16 v[68:71], v[168:171], v[210:213], v[68:71]
	v_mfma_f32_16x16x32_bf16 v[64:67], v[176:179], v[210:213], v[64:67]
	v_mfma_f32_16x16x32_bf16 v[116:119], v[172:175], v[188:191], v[116:119]
	v_mfma_f32_16x16x32_bf16 v[112:115], v[180:183], v[188:191], v[112:115]
	v_mfma_f32_16x16x32_bf16 v[100:103], v[172:175], v[196:199], v[100:103]
	v_mfma_f32_16x16x32_bf16 v[96:99], v[180:183], v[196:199], v[96:99]
	v_mfma_f32_16x16x32_bf16 v[84:87], v[172:175], v[206:209], v[84:87]
	v_mfma_f32_16x16x32_bf16 v[80:83], v[180:183], v[206:209], v[80:83]
	v_mfma_f32_16x16x32_bf16 v[68:71], v[172:175], v[214:217], v[68:71]
	v_mfma_f32_16x16x32_bf16 v[64:67], v[180:183], v[214:217], v[64:67]
	s_barrier
	s_add_u32 s100, s36, 0x80
	s_addc_u32 s101, s37, 0
	s_add_u32 s58, s36, 0x100080
	s_addc_u32 s59, s37, 0
	s_add_u32 s98, s38, 0x80
	s_addc_u32 s99, s39, 0
	ds_read_b128 v[184:187], v155 offset:49152
	ds_read_b128 v[188:191], v155 offset:50176
	s_add_i32 m0, s31, 0x18000
	ds_read_b128 v[192:195], v155 offset:51200
	global_load_lds_dwordx4 v130, s[100:101]
	s_add_i32 m0, s31, 0x1a000
	ds_read_b128 v[196:199], v155 offset:52224
	global_load_lds_dwordx4 v134, s[100:101]
	s_add_i32 m0, s31, 0x1c000
	ds_read_b128 v[202:205], v155 offset:53248
	global_load_lds_dwordx4 v130, s[58:59]
	s_add_i32 m0, s31, 0x1e000
	ds_read_b128 v[206:209], v155 offset:54272
	global_load_lds_dwordx4 v134, s[58:59]
	s_add_i32 m0, s31, 0x8000
	ds_read_b128 v[210:213], v155 offset:55296
	global_load_lds_dwordx4 v128, s[98:99]
	s_add_i32 m0, s31, 0xa000
	ds_read_b128 v[214:217], v155 offset:56320
	global_load_lds_dwordx4 v132, s[98:99]
	s_waitcnt vmcnt(8) lgkmcnt(0)
	s_barrier
	v_mfma_f32_16x16x32_bf16 v[60:63], v[144:147], v[184:187], v[60:63]
	v_mfma_f32_16x16x32_bf16 v[56:59], v[160:163], v[184:187], v[56:59]
	v_mfma_f32_16x16x32_bf16 v[44:47], v[144:147], v[192:195], v[44:47]
	v_mfma_f32_16x16x32_bf16 v[40:43], v[160:163], v[192:195], v[40:43]
	v_mfma_f32_16x16x32_bf16 v[28:31], v[144:147], v[202:205], v[28:31]
	v_mfma_f32_16x16x32_bf16 v[24:27], v[160:163], v[202:205], v[24:27]
	v_mfma_f32_16x16x32_bf16 v[12:15], v[144:147], v[210:213], v[12:15]
	v_mfma_f32_16x16x32_bf16 v[8:11], v[160:163], v[210:213], v[8:11]
	v_mfma_f32_16x16x32_bf16 v[60:63], v[156:159], v[188:191], v[60:63]
	v_mfma_f32_16x16x32_bf16 v[56:59], v[164:167], v[188:191], v[56:59]
	v_mfma_f32_16x16x32_bf16 v[44:47], v[156:159], v[196:199], v[44:47]
	v_mfma_f32_16x16x32_bf16 v[40:43], v[164:167], v[196:199], v[40:43]
	v_mfma_f32_16x16x32_bf16 v[28:31], v[156:159], v[206:209], v[28:31]
	v_mfma_f32_16x16x32_bf16 v[24:27], v[164:167], v[206:209], v[24:27]
	v_mfma_f32_16x16x32_bf16 v[12:15], v[156:159], v[214:217], v[12:15]
	v_mfma_f32_16x16x32_bf16 v[8:11], v[164:167], v[214:217], v[8:11]
	v_mfma_f32_16x16x32_bf16 v[52:55], v[168:171], v[184:187], v[52:55]
	v_mfma_f32_16x16x32_bf16 v[48:51], v[176:179], v[184:187], v[48:51]
	v_mfma_f32_16x16x32_bf16 v[36:39], v[168:171], v[192:195], v[36:39]
	v_mfma_f32_16x16x32_bf16 v[32:35], v[176:179], v[192:195], v[32:35]
	v_mfma_f32_16x16x32_bf16 v[20:23], v[168:171], v[202:205], v[20:23]
	v_mfma_f32_16x16x32_bf16 v[16:19], v[176:179], v[202:205], v[16:19]
	v_mfma_f32_16x16x32_bf16 v[4:7], v[168:171], v[210:213], v[4:7]
	v_mfma_f32_16x16x32_bf16 v[0:3], v[176:179], v[210:213], v[0:3]
	v_mfma_f32_16x16x32_bf16 v[52:55], v[172:175], v[188:191], v[52:55]
	v_mfma_f32_16x16x32_bf16 v[48:51], v[180:183], v[188:191], v[48:51]
	v_mfma_f32_16x16x32_bf16 v[36:39], v[172:175], v[196:199], v[36:39]
	v_mfma_f32_16x16x32_bf16 v[32:35], v[180:183], v[196:199], v[32:35]
	v_mfma_f32_16x16x32_bf16 v[20:23], v[172:175], v[206:209], v[20:23]
	v_mfma_f32_16x16x32_bf16 v[16:19], v[180:183], v[206:209], v[16:19]
	v_mfma_f32_16x16x32_bf16 v[4:7], v[172:175], v[214:217], v[4:7]
	v_mfma_f32_16x16x32_bf16 v[0:3], v[180:183], v[214:217], v[0:3]
	s_barrier
	s_add_i32 s57, s57, 2
	s_add_u32 s34, s34, 0x100
	s_addc_u32 s35, s35, 0
	s_add_u32 s55, s55, 0x100
	s_addc_u32 s56, s56, 0
	s_cmp_gt_u32 s57, 61
	s_cbranch_scc0 .LBB0_1299
	s_and_b64 vcc, exec, s[6:7]
	s_cbranch_vccz .LBB0_1302
	s_barrier

.LBB0_1409:
	ds_read_b128 v[128:131], v177 offset:0
	ds_read_b128 v[146:149], v177 offset:1024
	ds_read_b128 v[150:153], v177 offset:2048
	ds_read_b128 v[154:157], v177 offset:3072
	ds_read_b128 v[158:161], v178 offset:0
	ds_read_b128 v[162:165], v178 offset:1024
	ds_read_b128 v[166:169], v178 offset:2048
	ds_read_b128 v[170:173], v178 offset:3072
	s_add_i32 s70, s46, 2
	s_add_u32 s44, s42, 0x100
	s_addc_u32 s45, s43, 0
	s_cmp_eq_u32 s37, s46
	s_cselect_b32 s46, s40, s68
	s_cselect_b32 s49, s39, s45
	s_cselect_b32 s48, s38, s44
	s_cselect_b32 s47, s41, s69
	ds_read_b128 v[180:183], v179 offset:0
	ds_read_b128 v[184:187], v179 offset:1024
	ds_read_b128 v[188:191], v179 offset:2048
	ds_read_b128 v[192:195], v179 offset:3072
	ds_read_b128 v[196:199], v179 offset:4096
	ds_read_b128 v[202:205], v179 offset:5120
	s_add_i32 m0, s50, 0xc000
	ds_read_b128 v[206:209], v179 offset:6144
	global_load_lds_dwordx4 v140, s[42:43]
	s_add_i32 m0, s50, 0xe000
	ds_read_b128 v[210:213], v179 offset:7168
	global_load_lds_dwordx4 v142, s[42:43]
	s_waitcnt vmcnt(8) lgkmcnt(0)
	s_barrier
	v_mfma_f32_16x16x32_bf16 v[124:127], v[128:131], v[180:183], v[124:127]
	v_mfma_f32_16x16x32_bf16 v[120:123], v[150:153], v[180:183], v[120:123]
	v_mfma_f32_16x16x32_bf16 v[108:111], v[128:131], v[188:191], v[108:111]
	v_mfma_f32_16x16x32_bf16 v[104:107], v[150:153], v[188:191], v[104:107]
	v_mfma_f32_16x16x32_bf16 v[92:95], v[128:131], v[196:199], v[92:95]
	v_mfma_f32_16x16x32_bf16 v[88:91], v[150:153], v[196:199], v[88:91]
	v_mfma_f32_16x16x32_bf16 v[76:79], v[128:131], v[206:209], v[76:79]
	v_mfma_f32_16x16x32_bf16 v[72:75], v[150:153], v[206:209], v[72:75]
	v_mfma_f32_16x16x32_bf16 v[124:127], v[146:149], v[184:187], v[124:127]
	v_mfma_f32_16x16x32_bf16 v[120:123], v[154:157], v[184:187], v[120:123]
	v_mfma_f32_16x16x32_bf16 v[108:111], v[146:149], v[192:195], v[108:111]
	v_mfma_f32_16x16x32_bf16 v[104:107], v[154:157], v[192:195], v[104:107]
	v_mfma_f32_16x16x32_bf16 v[92:95], v[146:149], v[202:205], v[92:95]
	v_mfma_f32_16x16x32_bf16 v[88:91], v[154:157], v[202:205], v[88:91]
	v_mfma_f32_16x16x32_bf16 v[76:79], v[146:149], v[210:213], v[76:79]
	v_mfma_f32_16x16x32_bf16 v[72:75], v[154:157], v[210:213], v[72:75]
	v_mfma_f32_16x16x32_bf16 v[116:119], v[158:161], v[180:183], v[116:119]
	v_mfma_f32_16x16x32_bf16 v[112:115], v[166:169], v[180:183], v[112:115]
	v_mfma_f32_16x16x32_bf16 v[100:103], v[158:161], v[188:191], v[100:103]
	v_mfma_f32_16x16x32_bf16 v[96:99], v[166:169], v[188:191], v[96:99]
	v_mfma_f32_16x16x32_bf16 v[84:87], v[158:161], v[196:199], v[84:87]
	v_mfma_f32_16x16x32_bf16 v[80:83], v[166:169], v[196:199], v[80:83]
	v_mfma_f32_16x16x32_bf16 v[68:71], v[158:161], v[206:209], v[68:71]
	v_mfma_f32_16x16x32_bf16 v[64:67], v[166:169], v[206:209], v[64:67]
	v_mfma_f32_16x16x32_bf16 v[116:119], v[162:165], v[184:187], v[116:119]
	v_mfma_f32_16x16x32_bf16 v[112:115], v[170:173], v[184:187], v[112:115]
	v_mfma_f32_16x16x32_bf16 v[100:103], v[162:165], v[192:195], v[100:103]
	v_mfma_f32_16x16x32_bf16 v[96:99], v[170:173], v[192:195], v[96:99]
	v_mfma_f32_16x16x32_bf16 v[84:87], v[162:165], v[202:205], v[84:87]
	v_mfma_f32_16x16x32_bf16 v[80:83], v[170:173], v[202:205], v[80:83]
	v_mfma_f32_16x16x32_bf16 v[68:71], v[162:165], v[210:213], v[68:71]
	v_mfma_f32_16x16x32_bf16 v[64:67], v[170:173], v[210:213], v[64:67]
	s_barrier
	s_add_u32 s42, s46, 0x2b0000
	s_addc_u32 s43, s47, 0
	ds_read_b128 v[180:183], v179 offset:16384
	ds_read_b128 v[184:187], v179 offset:17408
	s_add_i32 m0, s50, 0x10000
	ds_read_b128 v[188:191], v179 offset:18432
	global_load_lds_dwordx4 v134, s[46:47]
	s_add_i32 m0, s50, 0x12000
	ds_read_b128 v[192:195], v179 offset:19456
	global_load_lds_dwordx4 v138, s[46:47]
	s_add_i32 m0, s50, 0x14000
	ds_read_b128 v[196:199], v179 offset:20480
	global_load_lds_dwordx4 v134, s[42:43]
	s_add_i32 m0, s50, 0x16000
	ds_read_b128 v[202:205], v179 offset:21504
	global_load_lds_dwordx4 v138, s[42:43]
	s_add_i32 m0, s50, 0x0
	ds_read_b128 v[206:209], v179 offset:22528
	global_load_lds_dwordx4 v132, s[48:49]
	s_add_i32 m0, s50, 0x2000
	ds_read_b128 v[210:213], v179 offset:23552
	global_load_lds_dwordx4 v136, s[48:49]
	s_waitcnt vmcnt(8) lgkmcnt(0)
	s_barrier
	v_mfma_f32_16x16x32_bf16 v[60:63], v[128:131], v[180:183], v[60:63]
	v_mfma_f32_16x16x32_bf16 v[56:59], v[150:153], v[180:183], v[56:59]
	v_mfma_f32_16x16x32_bf16 v[44:47], v[128:131], v[188:191], v[44:47]
	v_mfma_f32_16x16x32_bf16 v[40:43], v[150:153], v[188:191], v[40:43]
	v_mfma_f32_16x16x32_bf16 v[28:31], v[128:131], v[196:199], v[28:31]
	v_mfma_f32_16x16x32_bf16 v[24:27], v[150:153], v[196:199], v[24:27]
	v_mfma_f32_16x16x32_bf16 v[12:15], v[128:131], v[206:209], v[12:15]
	v_mfma_f32_16x16x32_bf16 v[8:11], v[150:153], v[206:209], v[8:11]
	v_mfma_f32_16x16x32_bf16 v[60:63], v[146:149], v[184:187], v[60:63]
	v_mfma_f32_16x16x32_bf16 v[56:59], v[154:157], v[184:187], v[56:59]
	v_mfma_f32_16x16x32_bf16 v[44:47], v[146:149], v[192:195], v[44:47]
	v_mfma_f32_16x16x32_bf16 v[40:43], v[154:157], v[192:195], v[40:43]
	v_mfma_f32_16x16x32_bf16 v[28:31], v[146:149], v[202:205], v[28:31]
	v_mfma_f32_16x16x32_bf16 v[24:27], v[154:157], v[202:205], v[24:27]
	v_mfma_f32_16x16x32_bf16 v[12:15], v[146:149], v[210:213], v[12:15]
	v_mfma_f32_16x16x32_bf16 v[8:11], v[154:157], v[210:213], v[8:11]
	v_mfma_f32_16x16x32_bf16 v[52:55], v[158:161], v[180:183], v[52:55]
	v_mfma_f32_16x16x32_bf16 v[48:51], v[166:169], v[180:183], v[48:51]
	v_mfma_f32_16x16x32_bf16 v[36:39], v[158:161], v[188:191], v[36:39]
	v_mfma_f32_16x16x32_bf16 v[32:35], v[166:169], v[188:191], v[32:35]
	v_mfma_f32_16x16x32_bf16 v[20:23], v[158:161], v[196:199], v[20:23]
	v_mfma_f32_16x16x32_bf16 v[16:19], v[166:169], v[196:199], v[16:19]
	v_mfma_f32_16x16x32_bf16 v[4:7], v[158:161], v[206:209], v[4:7]
	v_mfma_f32_16x16x32_bf16 v[0:3], v[166:169], v[206:209], v[0:3]
	v_mfma_f32_16x16x32_bf16 v[52:55], v[162:165], v[184:187], v[52:55]
	v_mfma_f32_16x16x32_bf16 v[48:51], v[170:173], v[184:187], v[48:51]
	v_mfma_f32_16x16x32_bf16 v[36:39], v[162:165], v[192:195], v[36:39]
	v_mfma_f32_16x16x32_bf16 v[32:35], v[170:173], v[192:195], v[32:35]
	v_mfma_f32_16x16x32_bf16 v[20:23], v[162:165], v[202:205], v[20:23]
	v_mfma_f32_16x16x32_bf16 v[16:19], v[170:173], v[202:205], v[16:19]
	v_mfma_f32_16x16x32_bf16 v[4:7], v[162:165], v[210:213], v[4:7]
	v_mfma_f32_16x16x32_bf16 v[0:3], v[170:173], v[210:213], v[0:3]
	s_barrier
	s_add_u32 s98, s48, 0x2b0000
	s_addc_u32 s99, s49, 0
	ds_read_b128 v[128:131], v177 offset:32768
	ds_read_b128 v[146:149], v177 offset:33792
	ds_read_b128 v[150:153], v177 offset:34816
	ds_read_b128 v[154:157], v177 offset:35840
	ds_read_b128 v[158:161], v178 offset:32768
	ds_read_b128 v[162:165], v178 offset:33792
	ds_read_b128 v[166:169], v178 offset:34816
	ds_read_b128 v[170:173], v178 offset:35840
	ds_read_b128 v[180:183], v179 offset:32768
	ds_read_b128 v[184:187], v179 offset:33792
	ds_read_b128 v[188:191], v179 offset:34816
	ds_read_b128 v[192:195], v179 offset:35840
	ds_read_b128 v[196:199], v179 offset:36864
	ds_read_b128 v[202:205], v179 offset:37888
	s_add_i32 m0, s50, 0x4000
	ds_read_b128 v[206:209], v179 offset:38912
	global_load_lds_dwordx4 v132, s[98:99]
	s_add_i32 m0, s50, 0x6000
	ds_read_b128 v[210:213], v179 offset:39936
	global_load_lds_dwordx4 v136, s[98:99]
	s_waitcnt vmcnt(8) lgkmcnt(0)
	s_barrier
	v_mfma_f32_16x16x32_bf16 v[124:127], v[128:131], v[180:183], v[124:127]
	v_mfma_f32_16x16x32_bf16 v[120:123], v[150:153], v[180:183], v[120:123]
	v_mfma_f32_16x16x32_bf16 v[108:111], v[128:131], v[188:191], v[108:111]
	v_mfma_f32_16x16x32_bf16 v[104:107], v[150:153], v[188:191], v[104:107]
	v_mfma_f32_16x16x32_bf16 v[92:95], v[128:131], v[196:199], v[92:95]
	v_mfma_f32_16x16x32_bf16 v[88:91], v[150:153], v[196:199], v[88:91]
	v_mfma_f32_16x16x32_bf16 v[76:79], v[128:131], v[206:209], v[76:79]
	v_mfma_f32_16x16x32_bf16 v[72:75], v[150:153], v[206:209], v[72:75]
	v_mfma_f32_16x16x32_bf16 v[124:127], v[146:149], v[184:187], v[124:127]
	v_mfma_f32_16x16x32_bf16 v[120:123], v[154:157], v[184:187], v[120:123]
	v_mfma_f32_16x16x32_bf16 v[108:111], v[146:149], v[192:195], v[108:111]
	v_mfma_f32_16x16x32_bf16 v[104:107], v[154:157], v[192:195], v[104:107]
	v_mfma_f32_16x16x32_bf16 v[92:95], v[146:149], v[202:205], v[92:95]
	v_mfma_f32_16x16x32_bf16 v[88:91], v[154:157], v[202:205], v[88:91]
	v_mfma_f32_16x16x32_bf16 v[76:79], v[146:149], v[210:213], v[76:79]
	v_mfma_f32_16x16x32_bf16 v[72:75], v[154:157], v[210:213], v[72:75]
	v_mfma_f32_16x16x32_bf16 v[116:119], v[158:161], v[180:183], v[116:119]
	v_mfma_f32_16x16x32_bf16 v[112:115], v[166:169], v[180:183], v[112:115]
	v_mfma_f32_16x16x32_bf16 v[100:103], v[158:161], v[188:191], v[100:103]
	v_mfma_f32_16x16x32_bf16 v[96:99], v[166:169], v[188:191], v[96:99]
	v_mfma_f32_16x16x32_bf16 v[84:87], v[158:161], v[196:199], v[84:87]
	v_mfma_f32_16x16x32_bf16 v[80:83], v[166:169], v[196:199], v[80:83]
	v_mfma_f32_16x16x32_bf16 v[68:71], v[158:161], v[206:209], v[68:71]
	v_mfma_f32_16x16x32_bf16 v[64:67], v[166:169], v[206:209], v[64:67]
	v_mfma_f32_16x16x32_bf16 v[116:119], v[162:165], v[184:187], v[116:119]
	v_mfma_f32_16x16x32_bf16 v[112:115], v[170:173], v[184:187], v[112:115]
	v_mfma_f32_16x16x32_bf16 v[100:103], v[162:165], v[192:195], v[100:103]
	v_mfma_f32_16x16x32_bf16 v[96:99], v[170:173], v[192:195], v[96:99]
	v_mfma_f32_16x16x32_bf16 v[84:87], v[162:165], v[202:205], v[84:87]
	v_mfma_f32_16x16x32_bf16 v[80:83], v[170:173], v[202:205], v[80:83]
	v_mfma_f32_16x16x32_bf16 v[68:71], v[162:165], v[210:213], v[68:71]
	v_mfma_f32_16x16x32_bf16 v[64:67], v[170:173], v[210:213], v[64:67]
	s_barrier
	s_add_u32 s100, s46, 0x80
	s_addc_u32 s101, s47, 0
	s_add_u32 s42, s46, 0x2b0080
	s_addc_u32 s43, s47, 0
	s_add_u32 s98, s48, 0x80
	s_addc_u32 s99, s49, 0
	ds_read_b128 v[180:183], v179 offset:49152
	ds_read_b128 v[184:187], v179 offset:50176
	s_add_i32 m0, s50, 0x18000
	ds_read_b128 v[188:191], v179 offset:51200
	global_load_lds_dwordx4 v134, s[100:101]
	s_add_i32 m0, s50, 0x1a000
	ds_read_b128 v[192:195], v179 offset:52224
	global_load_lds_dwordx4 v138, s[100:101]
	s_add_i32 m0, s50, 0x1c000
	ds_read_b128 v[196:199], v179 offset:53248
	global_load_lds_dwordx4 v134, s[42:43]
	s_add_i32 m0, s50, 0x1e000
	ds_read_b128 v[202:205], v179 offset:54272
	global_load_lds_dwordx4 v138, s[42:43]
	s_add_i32 m0, s50, 0x8000
	ds_read_b128 v[206:209], v179 offset:55296
	global_load_lds_dwordx4 v132, s[98:99]
	s_add_i32 m0, s50, 0xa000
	ds_read_b128 v[210:213], v179 offset:56320
	global_load_lds_dwordx4 v136, s[98:99]
	s_waitcnt vmcnt(8) lgkmcnt(0)
	s_barrier
	v_mfma_f32_16x16x32_bf16 v[60:63], v[128:131], v[180:183], v[60:63]
	v_mfma_f32_16x16x32_bf16 v[56:59], v[150:153], v[180:183], v[56:59]
	v_mfma_f32_16x16x32_bf16 v[44:47], v[128:131], v[188:191], v[44:47]
	v_mfma_f32_16x16x32_bf16 v[40:43], v[150:153], v[188:191], v[40:43]
	v_mfma_f32_16x16x32_bf16 v[28:31], v[128:131], v[196:199], v[28:31]
	v_mfma_f32_16x16x32_bf16 v[24:27], v[150:153], v[196:199], v[24:27]
	v_mfma_f32_16x16x32_bf16 v[12:15], v[128:131], v[206:209], v[12:15]
	v_mfma_f32_16x16x32_bf16 v[8:11], v[150:153], v[206:209], v[8:11]
	v_mfma_f32_16x16x32_bf16 v[60:63], v[146:149], v[184:187], v[60:63]
	v_mfma_f32_16x16x32_bf16 v[56:59], v[154:157], v[184:187], v[56:59]
	v_mfma_f32_16x16x32_bf16 v[44:47], v[146:149], v[192:195], v[44:47]
	v_mfma_f32_16x16x32_bf16 v[40:43], v[154:157], v[192:195], v[40:43]
	v_mfma_f32_16x16x32_bf16 v[28:31], v[146:149], v[202:205], v[28:31]
	v_mfma_f32_16x16x32_bf16 v[24:27], v[154:157], v[202:205], v[24:27]
	v_mfma_f32_16x16x32_bf16 v[12:15], v[146:149], v[210:213], v[12:15]
	v_mfma_f32_16x16x32_bf16 v[8:11], v[154:157], v[210:213], v[8:11]
	v_mfma_f32_16x16x32_bf16 v[52:55], v[158:161], v[180:183], v[52:55]
	v_mfma_f32_16x16x32_bf16 v[48:51], v[166:169], v[180:183], v[48:51]
	v_mfma_f32_16x16x32_bf16 v[36:39], v[158:161], v[188:191], v[36:39]
	v_mfma_f32_16x16x32_bf16 v[32:35], v[166:169], v[188:191], v[32:35]
	v_mfma_f32_16x16x32_bf16 v[20:23], v[158:161], v[196:199], v[20:23]
	v_mfma_f32_16x16x32_bf16 v[16:19], v[166:169], v[196:199], v[16:19]
	v_mfma_f32_16x16x32_bf16 v[4:7], v[158:161], v[206:209], v[4:7]
	v_mfma_f32_16x16x32_bf16 v[0:3], v[166:169], v[206:209], v[0:3]
	v_mfma_f32_16x16x32_bf16 v[52:55], v[162:165], v[184:187], v[52:55]
	v_mfma_f32_16x16x32_bf16 v[48:51], v[170:173], v[184:187], v[48:51]
	v_mfma_f32_16x16x32_bf16 v[36:39], v[162:165], v[192:195], v[36:39]
	v_mfma_f32_16x16x32_bf16 v[32:35], v[170:173], v[192:195], v[32:35]
	v_mfma_f32_16x16x32_bf16 v[20:23], v[162:165], v[202:205], v[20:23]
	v_mfma_f32_16x16x32_bf16 v[16:19], v[170:173], v[202:205], v[16:19]
	v_mfma_f32_16x16x32_bf16 v[4:7], v[162:165], v[210:213], v[4:7]
	v_mfma_f32_16x16x32_bf16 v[0:3], v[170:173], v[210:213], v[0:3]
	s_barrier
	s_add_u32 s68, s68, 0x100
	s_addc_u32 s69, s69, 0
	s_cmp_ge_i32 s70, s67
	s_mov_b64 s[42:43], s[44:45]
	s_mov_b32 s46, s70
	s_cbranch_scc0 .LBB0_1409
	s_and_b64 vcc, exec, s[14:15]
	s_cbranch_vccz .LBB0_1412
